# attention loops: row-sum v_pk_add_f32 split into scalar v_add_f32 pairs (packed fp32 is slower beside MFMAs)
# speedup vs baseline: 1.0117x; 1.0081x over previous
.LBB0_937:
	v_exp_f32_e32 v80, v80
	v_exp_f32_e32 v81, v81
	v_exp_f32_e32 v82, v82
	v_exp_f32_e32 v83, v83
	v_exp_f32_e32 v84, v84
	v_exp_f32_e32 v85, v85
	v_exp_f32_e32 v86, v86
	v_exp_f32_e32 v87, v87
	v_exp_f32_e32 v206, v64
	v_exp_f32_e32 v207, v65
	v_exp_f32_e32 v208, v66
	v_exp_f32_e32 v209, v67
	v_cvt_pk_bf16_f32 v64, v80, v81
	v_cvt_pk_bf16_f32 v65, v82, v83
	v_cvt_pk_bf16_f32 v66, v84, v85
	v_cvt_pk_bf16_f32 v67, v86, v87
	s_waitcnt lgkmcnt(0)
	v_exp_f32_e32 v88, v88
	v_exp_f32_e32 v89, v89
	v_mfma_f32_32x32x16_bf16 v[0:15], v[164:167], v[64:67], v[0:15]
	v_exp_f32_e32 v90, v90
	v_exp_f32_e32 v91, v91
	v_exp_f32_e32 v92, v92
	v_exp_f32_e32 v93, v93
	v_exp_f32_e32 v94, v94
	v_exp_f32_e32 v95, v95
	v_exp_f32_e32 v210, v68
	v_mfma_f32_32x32x16_bf16 v[16:31], v[148:151], v[64:67], v[16:31]
	v_exp_f32_e32 v211, v69
	v_exp_f32_e32 v212, v70
	v_exp_f32_e32 v213, v71
	v_cvt_pk_bf16_f32 v68, v88, v89
	v_cvt_pk_bf16_f32 v69, v90, v91
	v_cvt_pk_bf16_f32 v70, v92, v93
	v_cvt_pk_bf16_f32 v71, v94, v95
	v_add_f32_e32 v64, 0, v80
	v_add_f32_e32 v65, 0, v81
	v_exp_f32_e32 v214, v72
	v_mfma_f32_32x32x16_bf16 v[0:15], v[160:163], v[68:71], v[0:15]
	v_exp_f32_e32 v215, v73
	v_exp_f32_e32 v160, v74
	v_exp_f32_e32 v161, v75
	v_cvt_pk_bf16_f32 v72, v206, v207
	v_cvt_pk_bf16_f32 v73, v208, v209
	v_cvt_pk_bf16_f32 v74, v210, v211
	v_cvt_pk_bf16_f32 v75, v212, v213
	v_mfma_f32_32x32x16_bf16 v[16:31], v[144:147], v[68:71], v[16:31]
	v_add_f32_e64 v64, v206, v64
	v_add_f32_e64 v65, v207, v65
	v_exp_f32_e32 v162, v76
	v_add_f32_e32 v64, v82, v64
	v_add_f32_e32 v65, v83, v65
	v_exp_f32_e32 v163, v77
	v_add_f32_e32 v64, v208, v64
	v_add_f32_e32 v65, v209, v65
	v_cvt_pk_bf16_f32 v76, v214, v215
	v_add_f32_e32 v64, v84, v64
	v_add_f32_e32 v65, v85, v65
	v_mfma_f32_32x32x16_bf16 v[0:15], v[156:159], v[72:75], v[0:15]
	v_exp_f32_e32 v156, v78
	v_exp_f32_e32 v157, v79
	v_add_f32_e32 v64, v210, v64
	v_add_f32_e32 v65, v211, v65
	v_cvt_pk_bf16_f32 v77, v160, v161
	v_add_f32_e32 v64, v86, v64
	v_add_f32_e32 v65, v87, v65
	v_cvt_pk_bf16_f32 v78, v162, v163
	v_add_f32_e32 v64, v212, v64
	v_add_f32_e32 v65, v213, v65
	v_mfma_f32_32x32x16_bf16 v[16:31], v[140:143], v[72:75], v[16:31]
	v_add_f32_e64 v64, v88, v64
	v_add_f32_e64 v65, v89, v65
	v_cvt_pk_bf16_f32 v79, v156, v157
	v_add_f32_e64 v64, v214, v64
	v_add_f32_e64 v65, v215, v65
	s_add_i32 s17, s17, 0x8000
	v_add_f32_e32 v64, v90, v64
	v_add_f32_e32 v65, v91, v65
	v_lshl_add_u64 v[170:171], v[170:171], 0, s[94:95]
	v_add_f32_e32 v64, v160, v64
	v_add_f32_e32 v65, v161, v65
	v_mfma_f32_32x32x16_bf16 v[0:15], v[152:155], v[76:79], v[0:15]
	v_add_f32_e64 v64, v92, v64
	v_add_f32_e64 v65, v93, v65
	v_lshl_add_u64 v[172:173], v[172:173], 0, s[96:97]
	v_add_f32_e64 v64, v162, v64
	v_add_f32_e64 v65, v163, v65
	s_cmp_lg_u32 s17, 0x118000
	v_add_f32_e32 v64, v94, v64
	v_add_f32_e32 v65, v95, v65
	v_lshl_add_u64 v[174:175], v[174:175], 0, s[96:97]
	v_add_f32_e32 v64, v156, v64
	v_add_f32_e32 v65, v157, v65
	v_mfma_f32_32x32x16_bf16 v[16:31], v[136:139], v[76:79], v[16:31]
	v_add_f32_e32 v64, v64, v65
	v_mov_b32_e32 v65, v64
	s_nop 0
	v_add_f32_e32 v136, v179, v64
	v_add_f32_e32 v137, v178, v65
	s_cbranch_scc0 .LBB0_939
	v_mov_b32_e32 v177, v136
	s_branch .LBB0_926

.LBB0_962:
	v_exp_f32_e32 v232, v112
	v_exp_f32_e32 v233, v113
	v_exp_f32_e32 v96, v96
	v_exp_f32_e32 v97, v97
	v_exp_f32_e32 v114, v114
	v_exp_f32_e32 v115, v115
	v_exp_f32_e32 v98, v98
	v_exp_f32_e32 v99, v99
	v_add_f32_e32 v112, 0, v232
	v_add_f32_e32 v113, 0, v233
	v_exp_f32_e32 v116, v116
	v_exp_f32_e32 v117, v117
	v_add_f32_e32 v112, v96, v112
	v_add_f32_e32 v113, v97, v113
	v_exp_f32_e32 v100, v100
	v_exp_f32_e32 v101, v101
	v_add_f32_e32 v112, v114, v112
	v_add_f32_e32 v113, v115, v113
	v_exp_f32_e32 v118, v118
	v_exp_f32_e32 v119, v119
	v_add_f32_e32 v112, v98, v112
	v_add_f32_e32 v113, v99, v113
	v_exp_f32_e32 v102, v102
	v_exp_f32_e32 v103, v103
	v_add_f32_e32 v112, v116, v112
	v_add_f32_e32 v113, v117, v113
	v_exp_f32_e32 v120, v120
	v_exp_f32_e32 v121, v121
	v_add_f32_e32 v112, v100, v112
	v_add_f32_e32 v113, v101, v113
	v_exp_f32_e32 v248, v104
	v_exp_f32_e32 v249, v105
	v_add_f32_e32 v112, v118, v112
	v_add_f32_e32 v113, v119, v113
	v_exp_f32_e32 v122, v122
	v_exp_f32_e32 v123, v123
	v_add_f32_e32 v112, v102, v112
	v_add_f32_e32 v113, v103, v113
	v_exp_f32_e32 v250, v106
	v_exp_f32_e32 v251, v107
	v_add_f32_e32 v104, v120, v112
	v_add_f32_e32 v105, v121, v113
	v_exp_f32_e32 v106, v124
	v_exp_f32_e32 v107, v125
	v_exp_f32_e32 v124, v108
	v_exp_f32_e32 v125, v109
	v_exp_f32_e32 v252, v110
	v_exp_f32_e32 v253, v111
	v_cvt_pk_bf16_f32 v108, v232, v233
	v_cvt_pk_bf16_f32 v109, v114, v115
	v_cvt_pk_bf16_f32 v110, v116, v117
	v_cvt_pk_bf16_f32 v111, v118, v119
	v_add_f32_e32 v104, v248, v104
	v_add_f32_e32 v105, v249, v105
	s_waitcnt lgkmcnt(0)
	v_exp_f32_e32 v126, v126
	v_mfma_f32_32x32x16_bf16 v[0:15], v[188:191], v[108:111], v[0:15]
	v_add_f32_e64 v104, v122, v104
	v_add_f32_e64 v105, v123, v105
	v_exp_f32_e32 v127, v127
	v_add_f32_e32 v104, v250, v104
	v_add_f32_e32 v105, v251, v105
	v_cvt_pk_bf16_f32 v96, v96, v97
	v_add_f32_e32 v104, v106, v104
	v_add_f32_e32 v105, v107, v105
	v_cvt_pk_bf16_f32 v106, v106, v107
	v_add_f32_e32 v104, v124, v104
	v_add_f32_e32 v105, v125, v105
	v_mfma_f32_32x32x16_bf16 v[16:31], v[172:175], v[108:111], v[16:31]
	v_add_f32_e64 v104, v126, v104
	v_add_f32_e64 v105, v127, v105
	v_cvt_pk_bf16_f32 v107, v126, v127
	v_add_f32_e64 v104, v252, v104
	v_add_f32_e64 v105, v253, v105
	v_cvt_pk_bf16_f32 v97, v98, v99
	v_add_f32_e32 v112, v104, v105
	v_add_f32_e32 v113, v105, v104
	v_cvt_pk_bf16_f32 v104, v120, v121
	v_cvt_pk_bf16_f32 v105, v122, v123
	v_cvt_pk_bf16_f32 v98, v100, v101
	v_cvt_pk_bf16_f32 v99, v102, v103
	v_mfma_f32_32x32x16_bf16 v[0:15], v[184:187], v[104:107], v[0:15]
	v_cvt_pk_bf16_f32 v100, v248, v249
	v_cvt_pk_bf16_f32 v101, v250, v251
	v_cvt_pk_bf16_f32 v102, v124, v125
	v_cvt_pk_bf16_f32 v103, v252, v253
	v_add_u32_e32 v126, 0x2200, v247
	s_add_i32 s28, s28, 0x8000
	v_lshl_add_u64 v[206:207], v[206:207], 0, s[70:71]
	v_mfma_f32_32x32x16_bf16 v[16:31], v[168:171], v[104:107], v[16:31]
	v_lshl_add_u64 v[208:209], v[208:209], 0, s[94:95]
	v_lshl_add_u64 v[210:211], v[210:211], 0, s[94:95]
	s_cmp_lg_u32 s28, 0x118000
	v_mfma_f32_32x32x16_bf16 v[0:15], v[180:183], v[96:99], v[0:15]
	v_mfma_f32_32x32x16_bf16 v[16:31], v[164:167], v[96:99], v[16:31]
	v_mfma_f32_32x32x16_bf16 v[0:15], v[176:179], v[100:103], v[0:15]
	v_mfma_f32_32x32x16_bf16 v[16:31], v[160:163], v[100:103], v[16:31]
	ds_read_b64 v[176:177], v126
	ds_read_b64 v[178:179], v126 offset:16
	ds_read_b64 v[172:173], v126 offset:32
	ds_read_b64 v[174:175], v126 offset:48
	ds_read_b64 v[168:169], v126 offset:64
	ds_read_b64 v[170:171], v126 offset:80
	ds_read_b64 v[164:165], v126 offset:96
	ds_read_b64 v[166:167], v126 offset:112
	ds_read_b64 v[160:161], v126 offset:0x1100
	ds_read_b64 v[162:163], v126 offset:0x1110
	ds_read_b64 v[122:123], v126 offset:0x1120
	ds_read_b64 v[124:125], v126 offset:0x1130
	ds_read_b64 v[118:119], v126 offset:0x1140
	ds_read_b64 v[120:121], v126 offset:0x1150
	ds_read_b64 v[114:115], v126 offset:0x1160
	ds_read_b64 v[116:117], v126 offset:0x1170
	s_nop 0
	s_nop 0
	s_waitcnt lgkmcnt(14)
	v_mfma_f32_32x32x16_bf16 v[48:63], v[176:179], v[108:111], v[48:63]
	s_waitcnt lgkmcnt(6)
	v_mfma_f32_32x32x16_bf16 v[32:47], v[160:163], v[108:111], v[32:47]
	v_add_f32_e64 v160, v215, v112
	v_add_f32_e64 v161, v214, v113
	v_mfma_f32_32x32x16_bf16 v[48:63], v[172:175], v[104:107], v[48:63]
	s_waitcnt lgkmcnt(4)
	v_mfma_f32_32x32x16_bf16 v[32:47], v[122:125], v[104:107], v[32:47]
	v_mfma_f32_32x32x16_bf16 v[48:63], v[168:171], v[96:99], v[48:63]
	s_waitcnt lgkmcnt(2)
	v_mfma_f32_32x32x16_bf16 v[32:47], v[118:121], v[96:99], v[32:47]
	v_mfma_f32_32x32x16_bf16 v[48:63], v[164:167], v[100:103], v[48:63]
	s_waitcnt lgkmcnt(0)
	v_mfma_f32_32x32x16_bf16 v[32:47], v[114:117], v[100:103], v[32:47]
	s_cbranch_scc0 .LBB0_964
	v_mov_b32_e32 v213, v160
	s_branch .LBB0_955

.LBB0_982:
	v_exp_f32_e32 v232, v112
	v_exp_f32_e32 v233, v113
	v_exp_f32_e32 v96, v96
	v_exp_f32_e32 v97, v97
	v_exp_f32_e32 v114, v114
	v_exp_f32_e32 v115, v115
	v_exp_f32_e32 v98, v98
	v_exp_f32_e32 v99, v99
	v_add_f32_e32 v112, 0, v232
	v_add_f32_e32 v113, 0, v233
	v_exp_f32_e32 v116, v116
	v_exp_f32_e32 v117, v117
	v_add_f32_e32 v112, v96, v112
	v_add_f32_e32 v113, v97, v113
	v_exp_f32_e32 v100, v100
	v_exp_f32_e32 v101, v101
	v_add_f32_e32 v112, v114, v112
	v_add_f32_e32 v113, v115, v113
	v_exp_f32_e32 v118, v118
	v_exp_f32_e32 v119, v119
	v_add_f32_e32 v112, v98, v112
	v_add_f32_e32 v113, v99, v113
	v_exp_f32_e32 v102, v102
	v_exp_f32_e32 v103, v103
	v_add_f32_e32 v112, v116, v112
	v_add_f32_e32 v113, v117, v113
	v_exp_f32_e32 v120, v120
	v_exp_f32_e32 v121, v121
	v_add_f32_e32 v112, v100, v112
	v_add_f32_e32 v113, v101, v113
	v_exp_f32_e32 v250, v104
	v_exp_f32_e32 v251, v105
	v_add_f32_e32 v112, v118, v112
	v_add_f32_e32 v113, v119, v113
	v_exp_f32_e32 v122, v122
	v_exp_f32_e32 v123, v123
	v_add_f32_e32 v112, v102, v112
	v_add_f32_e32 v113, v103, v113
	v_exp_f32_e32 v252, v106
	v_exp_f32_e32 v253, v107
	v_add_f32_e32 v104, v120, v112
	v_add_f32_e32 v105, v121, v113
	v_exp_f32_e32 v106, v124
	v_exp_f32_e32 v107, v125
	v_exp_f32_e32 v124, v108
	v_exp_f32_e32 v125, v109
	v_exp_f32_e32 v234, v110
	v_exp_f32_e32 v235, v111
	v_cvt_pk_bf16_f32 v108, v232, v233
	v_cvt_pk_bf16_f32 v109, v114, v115
	v_cvt_pk_bf16_f32 v110, v116, v117
	v_cvt_pk_bf16_f32 v111, v118, v119
	v_add_f32_e32 v104, v250, v104
	v_add_f32_e32 v105, v251, v105
	s_waitcnt lgkmcnt(0)
	v_exp_f32_e32 v126, v126
	v_mfma_f32_32x32x16_bf16 v[0:15], v[188:191], v[108:111], v[0:15]
	v_add_f32_e64 v104, v122, v104
	v_add_f32_e64 v105, v123, v105
	v_exp_f32_e32 v127, v127
	v_add_f32_e32 v104, v252, v104
	v_add_f32_e32 v105, v253, v105
	v_cvt_pk_bf16_f32 v96, v96, v97
	v_add_f32_e32 v104, v106, v104
	v_add_f32_e32 v105, v107, v105
	v_cvt_pk_bf16_f32 v106, v106, v107
	v_add_f32_e32 v104, v124, v104
	v_add_f32_e32 v105, v125, v105
	v_mfma_f32_32x32x16_bf16 v[48:63], v[172:175], v[108:111], v[48:63]
	v_add_f32_e64 v104, v126, v104
	v_add_f32_e64 v105, v127, v105
	v_cvt_pk_bf16_f32 v107, v126, v127
	v_add_f32_e64 v104, v234, v104
	v_add_f32_e64 v105, v235, v105
	v_cvt_pk_bf16_f32 v97, v98, v99
	v_add_f32_e32 v112, v104, v105
	v_add_f32_e32 v113, v105, v104
	v_cvt_pk_bf16_f32 v104, v120, v121
	v_cvt_pk_bf16_f32 v105, v122, v123
	v_cvt_pk_bf16_f32 v98, v100, v101
	v_cvt_pk_bf16_f32 v99, v102, v103
	v_mfma_f32_32x32x16_bf16 v[0:15], v[184:187], v[104:107], v[0:15]
	v_cvt_pk_bf16_f32 v100, v250, v251
	v_cvt_pk_bf16_f32 v101, v252, v253
	v_cvt_pk_bf16_f32 v102, v124, v125
	v_cvt_pk_bf16_f32 v103, v234, v235
	v_add_u32_e32 v126, 0x2200, v249
	s_add_i32 s8, s8, 0x8000
	v_lshl_add_u64 v[204:205], v[204:205], 0, s[70:71]
	v_mfma_f32_32x32x16_bf16 v[48:63], v[168:171], v[104:107], v[48:63]
	v_lshl_add_u64 v[206:207], v[206:207], 0, s[94:95]
	v_lshl_add_u64 v[208:209], v[208:209], 0, s[94:95]
	s_cmp_lg_u32 s8, 0x118000
	v_mfma_f32_32x32x16_bf16 v[0:15], v[180:183], v[96:99], v[0:15]
	v_mfma_f32_32x32x16_bf16 v[48:63], v[164:167], v[96:99], v[48:63]
	v_mfma_f32_32x32x16_bf16 v[0:15], v[176:179], v[100:103], v[0:15]
	v_mfma_f32_32x32x16_bf16 v[48:63], v[160:163], v[100:103], v[48:63]
	ds_read_b64 v[176:177], v126
	ds_read_b64 v[178:179], v126 offset:16
	ds_read_b64 v[172:173], v126 offset:32
	ds_read_b64 v[174:175], v126 offset:48
	ds_read_b64 v[168:169], v126 offset:64
	ds_read_b64 v[170:171], v126 offset:80
	ds_read_b64 v[164:165], v126 offset:96
	ds_read_b64 v[166:167], v126 offset:112
	ds_read_b64 v[160:161], v126 offset:0x1100
	ds_read_b64 v[162:163], v126 offset:0x1110
	ds_read_b64 v[122:123], v126 offset:0x1120
	ds_read_b64 v[124:125], v126 offset:0x1130
	ds_read_b64 v[118:119], v126 offset:0x1140
	ds_read_b64 v[120:121], v126 offset:0x1150
	ds_read_b64 v[114:115], v126 offset:0x1160
	ds_read_b64 v[116:117], v126 offset:0x1170
	s_nop 0
	s_nop 0
	s_waitcnt lgkmcnt(14)
	v_mfma_f32_32x32x16_bf16 v[32:47], v[176:179], v[108:111], v[32:47]
	s_waitcnt lgkmcnt(6)
	v_mfma_f32_32x32x16_bf16 v[16:31], v[160:163], v[108:111], v[16:31]
	v_add_f32_e64 v160, v213, v112
	v_add_f32_e64 v161, v212, v113
	v_mfma_f32_32x32x16_bf16 v[32:47], v[172:175], v[104:107], v[32:47]
	s_waitcnt lgkmcnt(4)
	v_mfma_f32_32x32x16_bf16 v[16:31], v[122:125], v[104:107], v[16:31]
	v_mfma_f32_32x32x16_bf16 v[32:47], v[168:171], v[96:99], v[32:47]
	s_waitcnt lgkmcnt(2)
	v_mfma_f32_32x32x16_bf16 v[16:31], v[118:121], v[96:99], v[16:31]
	v_mfma_f32_32x32x16_bf16 v[32:47], v[164:167], v[100:103], v[32:47]
	s_waitcnt lgkmcnt(0)
	v_mfma_f32_32x32x16_bf16 v[16:31], v[114:117], v[100:103], v[16:31]
	s_cbranch_scc0 .LBB0_984
	v_mov_b32_e32 v211, v160
	s_branch .LBB0_975
